# P5: epilogue conv weights + row sumsq prefetched into spare LDS by LDS-DMA in the last K-iteration; epilogue reads them via ds_read (16 exposed global loads removed)
# speedup vs baseline: 1.0076x; 1.0015x over previous
.LBB0_639:
	s_add_i32 m0, s66, 0xc000
	ds_read_b128 v[52:55], v188
	ds_read_b128 v[56:59], v188 offset:1024
	ds_read_b128 v[60:63], v188 offset:2048
	ds_read_b128 v[64:67], v188 offset:3072
	ds_read_b128 v[72:75], v189
	ds_read_b128 v[76:79], v189 offset:1024
	ds_read_b128 v[80:83], v189 offset:2048
	ds_read_b128 v[84:87], v189 offset:3072
	s_add_u32 s60, s14, 0x1000
	s_addc_u32 s61, s15, 0
	s_cmp_eq_u32 s93, 60
	s_cselect_b32 s65, s11, s61
	s_cselect_b32 s64, s13, s60
	s_cselect_b32 s63, s53, s91
	s_cselect_b32 s62, s55, s90
	s_cbranch_scc0 .Lpf_skip
	v_mbcnt_lo_u32_b32 v224, -1, 0
	v_mbcnt_hi_u32_b32 v224, -1, v224
	s_cmp_lt_u32 s19, 0x800
	s_cbranch_scc0 .Lpf_ss
	v_and_b32_e32 v224, 31, v224
	v_lshlrev_b32_e32 v224, 4, v224
	s_lshl_b32 s3, s10, 9
	v_add_u32_e32 v224, s3, v224
	s_add_i32 m0, s19, 0x21000
	s_cmp_eq_u32 s19, 0
	s_cbranch_scc0 .Lpf_w1
	s_mov_b32 exec_lo, -1
	s_mov_b32 exec_hi, 0
	global_load_lds_dwordx4 v224, s[50:51]
	s_mov_b32 exec_lo, 0
	s_mov_b32 exec_hi, -1
	global_load_lds_dwordx4 v224, s[46:47]
	s_mov_b32 exec_lo, -1
	s_branch .Lpf_skip
.Lpf_w1:
	s_mov_b32 exec_lo, -1
	s_mov_b32 exec_hi, 0
	global_load_lds_dwordx4 v224, s[48:49]
	s_mov_b32 exec_lo, 0
	s_mov_b32 exec_hi, -1
	global_load_lds_dwordx4 v224, s[20:21]
	s_mov_b32 exec_lo, -1
	s_branch .Lpf_skip
.Lpf_ss:
	s_cmp_lt_u32 s19, 0x1800
	s_cbranch_scc0 .Lpf_skip
	s_lshr_b32 s3, s19, 4
	s_addk_i32 s3, 0xff80
	s_mul_i32 s16, s12, 0xfe
	s_add_i32 s16, s16, s3
	s_add_i32 s16, s16, -2
	v_add_u32_e32 v224, s16, v224
	v_med3_i32 v224, v224, 0, v192
	v_lshlrev_b32_e32 v224, 2, v224
	s_lshl_b32 s3, s3, 2
	s_add_i32 m0, s3, 0x21800
	s_nop 0
	global_load_lds_dword v224, s[28:29]
.Lpf_skip:
	s_add_i32 m0, s66, 0xc000
	ds_read_b128 v[180:183], v190
	ds_read_b128 v[196:199], v190 offset:1024
	ds_read_b128 v[200:203], v190 offset:2048
	ds_read_b128 v[204:207], v190 offset:3072
	ds_read_b128 v[208:211], v190 offset:4096
	ds_read_b128 v[212:215], v190 offset:5120
	ds_read_b128 v[216:219], v190 offset:6144
	ds_read_b128 v[220:223], v190 offset:7168
	global_load_lds_dwordx4 v172, s[14:15]
	s_add_i32 m0, s66, 0xe000
	s_nop 0
	global_load_lds_dwordx4 v174, s[14:15]
	s_waitcnt vmcnt(8)
	s_waitcnt lgkmcnt(0)
	s_setprio 1
	s_barrier
	v_mfma_f32_16x16x32_bf16 v[156:159], v[52:55], v[180:183], v[156:159]
	v_mfma_f32_16x16x32_bf16 v[152:155], v[60:63], v[180:183], v[152:155]
	v_mfma_f32_16x16x32_bf16 v[140:143], v[52:55], v[200:203], v[140:143]
	v_mfma_f32_16x16x32_bf16 v[136:139], v[60:63], v[200:203], v[136:139]
	v_mfma_f32_16x16x32_bf16 v[124:127], v[52:55], v[208:211], v[124:127]
	v_mfma_f32_16x16x32_bf16 v[120:123], v[60:63], v[208:211], v[120:123]
	v_mfma_f32_16x16x32_bf16 v[108:111], v[52:55], v[216:219], v[108:111]
	v_mfma_f32_16x16x32_bf16 v[104:107], v[60:63], v[216:219], v[104:107]
	v_mfma_f32_16x16x32_bf16 v[156:159], v[56:59], v[196:199], v[156:159]
	v_mfma_f32_16x16x32_bf16 v[152:155], v[64:67], v[196:199], v[152:155]
	v_mfma_f32_16x16x32_bf16 v[140:143], v[56:59], v[204:207], v[140:143]
	v_mfma_f32_16x16x32_bf16 v[136:139], v[64:67], v[204:207], v[136:139]
	v_mfma_f32_16x16x32_bf16 v[124:127], v[56:59], v[212:215], v[124:127]
	v_mfma_f32_16x16x32_bf16 v[120:123], v[64:67], v[212:215], v[120:123]
	v_mfma_f32_16x16x32_bf16 v[108:111], v[56:59], v[220:223], v[108:111]
	v_mfma_f32_16x16x32_bf16 v[104:107], v[64:67], v[220:223], v[104:107]
	v_mfma_f32_16x16x32_bf16 v[144:147], v[72:75], v[180:183], v[144:147]
	v_mfma_f32_16x16x32_bf16 v[148:151], v[80:83], v[180:183], v[148:151]
	v_mfma_f32_16x16x32_bf16 v[128:131], v[72:75], v[200:203], v[128:131]
	v_mfma_f32_16x16x32_bf16 v[132:135], v[80:83], v[200:203], v[132:135]
	v_mfma_f32_16x16x32_bf16 v[112:115], v[72:75], v[208:211], v[112:115]
	v_mfma_f32_16x16x32_bf16 v[116:119], v[80:83], v[208:211], v[116:119]
	v_mfma_f32_16x16x32_bf16 v[96:99], v[72:75], v[216:219], v[96:99]
	v_mfma_f32_16x16x32_bf16 v[100:103], v[80:83], v[216:219], v[100:103]
	v_mfma_f32_16x16x32_bf16 v[144:147], v[76:79], v[196:199], v[144:147]
	v_mfma_f32_16x16x32_bf16 v[148:151], v[84:87], v[196:199], v[148:151]
	v_mfma_f32_16x16x32_bf16 v[128:131], v[76:79], v[204:207], v[128:131]
	v_mfma_f32_16x16x32_bf16 v[132:135], v[84:87], v[204:207], v[132:135]
	v_mfma_f32_16x16x32_bf16 v[112:115], v[76:79], v[212:215], v[112:115]
	v_mfma_f32_16x16x32_bf16 v[116:119], v[84:87], v[212:215], v[116:119]
	v_mfma_f32_16x16x32_bf16 v[96:99], v[76:79], v[220:223], v[96:99]
	v_mfma_f32_16x16x32_bf16 v[100:103], v[84:87], v[220:223], v[100:103]
	s_barrier
	s_setprio 0
	s_add_i32 s3, s80, s19
	s_mov_b32 m0, s3
	ds_read_b128 v[180:183], v190 offset:16384
	ds_read_b128 v[196:199], v190 offset:17408
	ds_read_b128 v[200:203], v190 offset:18432
	ds_read_b128 v[204:207], v190 offset:19456
	ds_read_b128 v[208:211], v190 offset:20480
	ds_read_b128 v[212:215], v190 offset:21504
	ds_read_b128 v[216:219], v190 offset:22528
	ds_read_b128 v[220:223], v190 offset:23552
	global_load_lds_dwordx4 v162, s[62:63]
	s_add_i32 m0, s3, 0x2000
	s_add_u32 s14, s62, 0x100000
	s_addc_u32 s15, s63, 0
	global_load_lds_dwordx4 v166, s[62:63]
	s_add_i32 s3, s81, s19
	s_mov_b32 m0, s3
	s_nop 0
	global_load_lds_dwordx4 v162, s[14:15]
	s_add_i32 m0, s3, 0x2000
	s_nop 0
	global_load_lds_dwordx4 v166, s[14:15]
	s_mov_b32 m0, s66
	s_nop 0
	global_load_lds_dwordx4 v160, s[64:65]
	s_mov_b32 m0, s67
	s_nop 0
	global_load_lds_dwordx4 v164, s[64:65]
	s_waitcnt vmcnt(8)
	s_waitcnt lgkmcnt(0)
	s_setprio 1
	s_barrier
	v_mfma_f32_16x16x32_bf16 v[92:95], v[52:55], v[180:183], v[92:95]
	v_mfma_f32_16x16x32_bf16 v[88:91], v[60:63], v[180:183], v[88:91]
	v_mfma_f32_16x16x32_bf16 v[44:47], v[52:55], v[200:203], v[44:47]
	v_mfma_f32_16x16x32_bf16 v[40:43], v[60:63], v[200:203], v[40:43]
	v_mfma_f32_16x16x32_bf16 v[28:31], v[52:55], v[208:211], v[28:31]
	v_mfma_f32_16x16x32_bf16 v[24:27], v[60:63], v[208:211], v[24:27]
	v_mfma_f32_16x16x32_bf16 v[12:15], v[52:55], v[216:219], v[12:15]
	v_mfma_f32_16x16x32_bf16 v[8:11], v[60:63], v[216:219], v[8:11]
	v_mfma_f32_16x16x32_bf16 v[92:95], v[56:59], v[196:199], v[92:95]
	v_mfma_f32_16x16x32_bf16 v[88:91], v[64:67], v[196:199], v[88:91]
	v_mfma_f32_16x16x32_bf16 v[44:47], v[56:59], v[204:207], v[44:47]
	v_mfma_f32_16x16x32_bf16 v[40:43], v[64:67], v[204:207], v[40:43]
	v_mfma_f32_16x16x32_bf16 v[28:31], v[56:59], v[212:215], v[28:31]
	v_mfma_f32_16x16x32_bf16 v[24:27], v[64:67], v[212:215], v[24:27]
	v_mfma_f32_16x16x32_bf16 v[12:15], v[56:59], v[220:223], v[12:15]
	v_mfma_f32_16x16x32_bf16 v[8:11], v[64:67], v[220:223], v[8:11]
	v_mfma_f32_16x16x32_bf16 v[48:51], v[72:75], v[180:183], v[48:51]
	v_mfma_f32_16x16x32_bf16 v[32:35], v[72:75], v[200:203], v[32:35]
	v_mfma_f32_16x16x32_bf16 v[36:39], v[80:83], v[200:203], v[36:39]
	v_mfma_f32_16x16x32_bf16 v[16:19], v[72:75], v[208:211], v[16:19]
	v_mfma_f32_16x16x32_bf16 v[20:23], v[80:83], v[208:211], v[20:23]
	v_mfma_f32_16x16x32_bf16 v[0:3], v[72:75], v[216:219], v[0:3]
	v_mfma_f32_16x16x32_bf16 v[4:7], v[80:83], v[216:219], v[4:7]
	v_mfma_f32_16x16x32_bf16 v[48:51], v[76:79], v[196:199], v[48:51]
	v_mfma_f32_16x16x32_bf16 v[52:55], v[80:83], v[180:183], v[68:71]
	v_mfma_f32_16x16x32_bf16 v[32:35], v[76:79], v[204:207], v[32:35]
	v_mfma_f32_16x16x32_bf16 v[36:39], v[84:87], v[204:207], v[36:39]
	v_mfma_f32_16x16x32_bf16 v[16:19], v[76:79], v[212:215], v[16:19]
	v_mfma_f32_16x16x32_bf16 v[20:23], v[84:87], v[212:215], v[20:23]
	v_mfma_f32_16x16x32_bf16 v[0:3], v[76:79], v[220:223], v[0:3]
	v_mfma_f32_16x16x32_bf16 v[4:7], v[84:87], v[220:223], v[4:7]
	v_mfma_f32_16x16x32_bf16 v[52:55], v[84:87], v[196:199], v[52:55]
	s_barrier
	s_setprio 0
	s_add_i32 s3, 0, 0x18000
	s_add_i32 s16, 0, 0x1c000
	v_add_u32_e32 v68, s3, v171
	v_add_u32_e32 v84, s16, v171
	s_add_u32 s14, s64, 0x80000
	s_addc_u32 s15, s65, 0
	s_mov_b32 m0, s70
	ds_read_b128 v[56:59], v68
	ds_read_b128 v[60:63], v68 offset:1024
	ds_read_b128 v[64:67], v68 offset:2048
	ds_read_b128 v[68:71], v68 offset:3072
	ds_read_b128 v[72:75], v84
	ds_read_b128 v[76:79], v84 offset:1024
	ds_read_b128 v[80:83], v84 offset:2048
	ds_read_b128 v[84:87], v84 offset:3072
	ds_read_b128 v[180:183], v190 offset:32768
	ds_read_b128 v[196:199], v190 offset:33792
	ds_read_b128 v[200:203], v190 offset:34816
	ds_read_b128 v[204:207], v190 offset:35840
	ds_read_b128 v[208:211], v190 offset:36864
	ds_read_b128 v[212:215], v190 offset:37888
	ds_read_b128 v[216:219], v190 offset:38912
	ds_read_b128 v[220:223], v190 offset:39936
	global_load_lds_dwordx4 v160, s[14:15]
	s_mov_b32 m0, s71
	s_nop 0
	global_load_lds_dwordx4 v164, s[14:15]
	s_waitcnt vmcnt(8)
	s_waitcnt lgkmcnt(0)
	s_setprio 1
	s_barrier
	v_mfma_f32_16x16x32_bf16 v[156:159], v[56:59], v[180:183], v[156:159]
	v_mfma_f32_16x16x32_bf16 v[152:155], v[64:67], v[180:183], v[152:155]
	v_mfma_f32_16x16x32_bf16 v[140:143], v[56:59], v[200:203], v[140:143]
	v_mfma_f32_16x16x32_bf16 v[136:139], v[64:67], v[200:203], v[136:139]
	v_mfma_f32_16x16x32_bf16 v[124:127], v[56:59], v[208:211], v[124:127]
	v_mfma_f32_16x16x32_bf16 v[120:123], v[64:67], v[208:211], v[120:123]
	v_mfma_f32_16x16x32_bf16 v[108:111], v[56:59], v[216:219], v[108:111]
	v_mfma_f32_16x16x32_bf16 v[104:107], v[64:67], v[216:219], v[104:107]
	v_mfma_f32_16x16x32_bf16 v[156:159], v[60:63], v[196:199], v[156:159]
	v_mfma_f32_16x16x32_bf16 v[152:155], v[68:71], v[196:199], v[152:155]
	v_mfma_f32_16x16x32_bf16 v[140:143], v[60:63], v[204:207], v[140:143]
	v_mfma_f32_16x16x32_bf16 v[136:139], v[68:71], v[204:207], v[136:139]
	v_mfma_f32_16x16x32_bf16 v[124:127], v[60:63], v[212:215], v[124:127]
	v_mfma_f32_16x16x32_bf16 v[120:123], v[68:71], v[212:215], v[120:123]
	v_mfma_f32_16x16x32_bf16 v[108:111], v[60:63], v[220:223], v[108:111]
	v_mfma_f32_16x16x32_bf16 v[104:107], v[68:71], v[220:223], v[104:107]
	v_mfma_f32_16x16x32_bf16 v[144:147], v[72:75], v[180:183], v[144:147]
	v_mfma_f32_16x16x32_bf16 v[148:151], v[80:83], v[180:183], v[148:151]
	v_mfma_f32_16x16x32_bf16 v[128:131], v[72:75], v[200:203], v[128:131]
	v_mfma_f32_16x16x32_bf16 v[132:135], v[80:83], v[200:203], v[132:135]
	v_mfma_f32_16x16x32_bf16 v[112:115], v[72:75], v[208:211], v[112:115]
	v_mfma_f32_16x16x32_bf16 v[116:119], v[80:83], v[208:211], v[116:119]
	v_mfma_f32_16x16x32_bf16 v[96:99], v[72:75], v[216:219], v[96:99]
	v_mfma_f32_16x16x32_bf16 v[100:103], v[80:83], v[216:219], v[100:103]
	v_mfma_f32_16x16x32_bf16 v[144:147], v[76:79], v[196:199], v[144:147]
	v_mfma_f32_16x16x32_bf16 v[148:151], v[84:87], v[196:199], v[148:151]
	v_mfma_f32_16x16x32_bf16 v[128:131], v[76:79], v[204:207], v[128:131]
	v_mfma_f32_16x16x32_bf16 v[132:135], v[84:87], v[204:207], v[132:135]
	v_mfma_f32_16x16x32_bf16 v[112:115], v[76:79], v[212:215], v[112:115]
	v_mfma_f32_16x16x32_bf16 v[116:119], v[84:87], v[212:215], v[116:119]
	v_mfma_f32_16x16x32_bf16 v[96:99], v[76:79], v[220:223], v[96:99]
	v_mfma_f32_16x16x32_bf16 v[100:103], v[84:87], v[220:223], v[100:103]
	s_barrier
	s_setprio 0
	s_add_i32 m0, s19, 0x17800
	ds_read_b128 v[180:183], v190 offset:49152
	ds_read_b128 v[196:199], v190 offset:50176
	ds_read_b128 v[200:203], v190 offset:51200
	ds_read_b128 v[204:207], v190 offset:52224
	ds_read_b128 v[208:211], v190 offset:53248
	ds_read_b128 v[212:215], v190 offset:54272
	ds_read_b128 v[216:219], v190 offset:55296
	ds_read_b128 v[220:223], v190 offset:56320
	global_load_lds_dwordx4 v162, s[62:63] offset:2048
	s_add_i32 m0, s19, 0x19800
	s_add_u32 s14, s62, 0x100800
	s_addc_u32 s15, s63, 0
	global_load_lds_dwordx4 v166, s[62:63] offset:2048
	s_add_i32 m0, s19, 0x1c000
	s_nop 0
	global_load_lds_dwordx4 v162, s[14:15]
	s_add_i32 m0, s19, 0x1e000
	s_nop 0
	global_load_lds_dwordx4 v166, s[14:15]
	s_add_i32 m0, s75, 0xfffff800
	s_nop 0
	global_load_lds_dwordx4 v160, s[64:65] offset:2048
	s_add_i32 m0, s76, 0xfffff800
	s_nop 0
	global_load_lds_dwordx4 v164, s[64:65] offset:2048
	s_waitcnt vmcnt(8)
	s_waitcnt lgkmcnt(0)
	s_setprio 1
	s_barrier
	v_mfma_f32_16x16x32_bf16 v[92:95], v[56:59], v[180:183], v[92:95]
	v_mfma_f32_16x16x32_bf16 v[88:91], v[64:67], v[180:183], v[88:91]
	v_mfma_f32_16x16x32_bf16 v[44:47], v[56:59], v[200:203], v[44:47]
	v_mfma_f32_16x16x32_bf16 v[40:43], v[64:67], v[200:203], v[40:43]
	v_mfma_f32_16x16x32_bf16 v[28:31], v[56:59], v[208:211], v[28:31]
	v_mfma_f32_16x16x32_bf16 v[24:27], v[64:67], v[208:211], v[24:27]
	v_mfma_f32_16x16x32_bf16 v[12:15], v[56:59], v[216:219], v[12:15]
	v_mfma_f32_16x16x32_bf16 v[8:11], v[64:67], v[216:219], v[8:11]
	v_mfma_f32_16x16x32_bf16 v[92:95], v[60:63], v[196:199], v[92:95]
	v_mfma_f32_16x16x32_bf16 v[88:91], v[68:71], v[196:199], v[88:91]
	v_mfma_f32_16x16x32_bf16 v[44:47], v[60:63], v[204:207], v[44:47]
	v_mfma_f32_16x16x32_bf16 v[40:43], v[68:71], v[204:207], v[40:43]
	v_mfma_f32_16x16x32_bf16 v[28:31], v[60:63], v[212:215], v[28:31]
	v_mfma_f32_16x16x32_bf16 v[24:27], v[68:71], v[212:215], v[24:27]
	v_mfma_f32_16x16x32_bf16 v[12:15], v[60:63], v[220:223], v[12:15]
	v_mfma_f32_16x16x32_bf16 v[8:11], v[68:71], v[220:223], v[8:11]
	v_mfma_f32_16x16x32_bf16 v[48:51], v[72:75], v[180:183], v[48:51]
	v_mfma_f32_16x16x32_bf16 v[52:55], v[80:83], v[180:183], v[52:55]
	v_mfma_f32_16x16x32_bf16 v[32:35], v[72:75], v[200:203], v[32:35]
	v_mfma_f32_16x16x32_bf16 v[36:39], v[80:83], v[200:203], v[36:39]
	v_mfma_f32_16x16x32_bf16 v[16:19], v[72:75], v[208:211], v[16:19]
	v_mfma_f32_16x16x32_bf16 v[20:23], v[80:83], v[208:211], v[20:23]
	v_mfma_f32_16x16x32_bf16 v[0:3], v[72:75], v[216:219], v[0:3]
	v_mfma_f32_16x16x32_bf16 v[4:7], v[80:83], v[216:219], v[4:7]
	v_mfma_f32_16x16x32_bf16 v[48:51], v[76:79], v[196:199], v[48:51]
	v_mfma_f32_16x16x32_bf16 v[68:71], v[84:87], v[196:199], v[52:55]
	v_mfma_f32_16x16x32_bf16 v[32:35], v[76:79], v[204:207], v[32:35]
	s_add_i32 s93, s93, 2
	v_mfma_f32_16x16x32_bf16 v[36:39], v[84:87], v[204:207], v[36:39]
	s_add_u32 s90, s90, 0x1000
	v_mfma_f32_16x16x32_bf16 v[16:19], v[76:79], v[212:215], v[16:19]
	s_addc_u32 s91, s91, 0
	v_mfma_f32_16x16x32_bf16 v[20:23], v[84:87], v[212:215], v[20:23]
	s_cmp_gt_u32 s93, 61
	v_mfma_f32_16x16x32_bf16 v[0:3], v[76:79], v[220:223], v[0:3]
	s_mov_b64 s[14:15], s[60:61]
	v_mfma_f32_16x16x32_bf16 v[4:7], v[84:87], v[220:223], v[4:7]
	s_barrier
	s_setprio 0
	s_cbranch_scc0 .LBB0_639
	s_and_b64 vcc, exec, s[42:43]
	s_cbranch_vccz .LBB0_642
	s_barrier
.LBB0_642:
	s_mul_i32 s53, s12, 0xfe
	v_add_u32_e32 v181, s53, v184
	v_add_u32_e32 v204, 16, v181
	v_add_u32_e32 v202, 32, v181
	v_add_u32_e32 v200, 48, v181
	v_add_u32_e32 v198, 64, v181
	v_add_u32_e32 v196, 0x50, v181
	v_add_u32_e32 v194, 0x60, v181
	v_add_u32_e32 v193, 0x70, v181
	s_lshl_b32 s3, s10, 7
	s_or_b32 s12, s3, s74
	v_or_b32_e32 v52, s12, v170
	v_ashrrev_i32_e32 v53, 31, v52
	v_lshlrev_b64 v[52:53], 2, v[52:53]
	v_mov_b32_e32 v229, v52
	v_lshlrev_b32_e32 v207, 2, v184
	v_add_u32_e32 v207, 0x21808, v207
	v_or_b32_e32 v208, s74, v170
	v_lshlrev_b32_e32 v208, 2, v208
	v_add_u32_e32 v208, 0x21000, v208
	ds_read_b32 v180, v207 offset:448
	ds_read_b32 v168, v207
	ds_read_b128 v[56:59], v208
	ds_read_b128 v[76:79], v208 offset:16
	ds_read_b128 v[60:63], v208 offset:512
	ds_read_b128 v[80:83], v208 offset:528
	ds_read_b128 v[64:67], v208 offset:1024
	ds_read_b128 v[84:87], v208 offset:1040
	ds_read_b128 v[52:55], v208 offset:1536
	ds_read_b128 v[72:75], v208 offset:1552
	ds_read_b32 v206, v207 offset:64
	ds_read_b32 v205, v207 offset:128
	ds_read_b32 v203, v207 offset:192
	ds_read_b32 v201, v207 offset:256
	ds_read_b32 v199, v207 offset:320
	ds_read_b32 v197, v207 offset:384
	s_waitcnt lgkmcnt(0)
	v_fmamk_f32 v180, v180, 0x39800000, v191
	v_rsq_f32_e32 v180, v180
	s_and_saveexec_b64 s[10:11], s[44:45]
	s_cbranch_execz .LBB0_644
	v_pk_mul_f32 v[208:209], v[12:13], v[180:181] op_sel_hi:[1,0]
	v_pk_mul_f32 v[210:211], v[14:15], v[180:181] op_sel_hi:[1,0]
	ds_write_b128 v186, v[208:211]
	v_pk_mul_f32 v[208:209], v[8:9], v[180:181] op_sel_hi:[1,0]
	v_pk_mul_f32 v[210:211], v[10:11], v[180:181] op_sel_hi:[1,0]
	ds_write_b128 v187, v[208:211]
